# dense softmax: cross-half max/sum exchanges deferred to the rare path / unit end
# baseline (speedup 1.0000x reference)
; __device__ __forceinline__ void partialSM(f32x16& p0, f32x16& p1, float& m_reg, float& mn, float& alpha) {
;   constexpr float C = SCALE * 1.4426950408889634f;
;   float pmax = p0[0];
; #pragma unroll
;   for (int r = 1; r < 16; ++r) pmax = fmaxf(pmax, p0[r]);
; #pragma unroll
;   for (int r = 0; r < 16; ++r) pmax = fmaxf(pmax, p1[r]);
;   { auto rr = __builtin_amdgcn_permlane32_swap(__float_as_uint(pmax), __float_as_uint(pmax), false, false);
;     pmax = fmaxf(__uint_as_float(rr[0]), __uint_as_float(rr[1])); }
;   if (__builtin_expect(__all(pmax - m_reg <= THR / SCALE), 1)) { mn = m_reg; alpha = 1.f; }
;   else { mn = fmaxf(m_reg, pmax); alpha = __builtin_amdgcn_exp2f((m_reg - mn) * C); m_reg = mn; }
.Lda_y0:
	s_barrier
	v_max3_f32 v190, v80, v81, v82
	v_max3_f32 v191, v64, v65, v66
	v_max3_f32 v190, v190, v83, v84
	v_max3_f32 v191, v191, v67, v68
	v_max3_f32 v190, v190, v85, v86
	v_max3_f32 v191, v191, v69, v70
	v_max3_f32 v190, v190, v87, v88
	v_max3_f32 v191, v191, v71, v72
	v_max3_f32 v190, v190, v89, v90
	v_max3_f32 v191, v191, v73, v74
	v_max3_f32 v190, v190, v91, v92
	v_max3_f32 v191, v191, v75, v76
	v_max3_f32 v190, v190, v93, v94
	v_max3_f32 v191, v191, v77, v78
	v_max3_f32 v190, v190, v95, v79
	v_max_f32_e32 v190, v190, v191
	v_sub_f32_e32 v215, v190, v174
	v_cmp_ge_f32_e32 vcc, s86, v215
	s_nop 3
	s_cmp_eq_u64 vcc, exec
	s_cbranch_scc1 .Lda_common_0
	v_mov_b32_e32 v191, v190
	s_nop 1
	v_permlane32_swap_b32_e32 v190, v191
	s_nop 0
	v_max_f32_e32 v212, v190, v191
	v_max_f32_e32 v191, v174, v212
	v_sub_f32_e32 v215, v174, v191
	v_mul_f32_e32 v215, s92, v215
	v_exp_f32_e32 v213, v215
	v_mov_b32_e32 v174, v191
	v_mul_f32_e32 v214, 0xbe0293ee, v174
	v_mul_f32_e32 v175, v175, v213
	s_and_saveexec_b64 s[12:13], s[40:41]
	ds_write_b32 v199, v213 offset:128
	s_or_b64 exec, exec, s[12:13]
	s_waitcnt lgkmcnt(0)
	v_add_u32_e32 v215, v99, v96
	ds_read_b128 v[228:231], v215 offset:128
	ds_read_b128 v[232:235], v215 offset:160
	ds_read_b128 v[236:239], v215 offset:192
	ds_read_b128 v[240:243], v215 offset:224
	s_waitcnt lgkmcnt(0)
	v_pk_mul_f32 v[0:1], v[0:1], v[228:229]
	v_pk_mul_f32 v[2:3], v[2:3], v[230:231]
	v_pk_mul_f32 v[4:5], v[4:5], v[232:233]
	v_pk_mul_f32 v[6:7], v[6:7], v[234:235]
	v_pk_mul_f32 v[8:9], v[8:9], v[236:237]
	v_pk_mul_f32 v[10:11], v[10:11], v[238:239]
	v_pk_mul_f32 v[12:13], v[12:13], v[240:241]
	v_pk_mul_f32 v[14:15], v[14:15], v[242:243]
	v_pk_mul_f32 v[48:49], v[48:49], v[228:229]
	v_pk_mul_f32 v[50:51], v[50:51], v[230:231]
	v_pk_mul_f32 v[52:53], v[52:53], v[232:233]
	v_pk_mul_f32 v[54:55], v[54:55], v[234:235]
	v_pk_mul_f32 v[56:57], v[56:57], v[236:237]
	v_pk_mul_f32 v[58:59], v[58:59], v[238:239]
	v_pk_mul_f32 v[60:61], v[60:61], v[240:241]
	v_pk_mul_f32 v[62:63], v[62:63], v[242:243]
	v_pk_mul_f32 v[32:33], v[32:33], v[228:229]
	v_pk_mul_f32 v[34:35], v[34:35], v[230:231]
	v_pk_mul_f32 v[36:37], v[36:37], v[232:233]
	v_pk_mul_f32 v[38:39], v[38:39], v[234:235]
	v_pk_mul_f32 v[40:41], v[40:41], v[236:237]
	v_pk_mul_f32 v[42:43], v[42:43], v[238:239]
	v_pk_mul_f32 v[44:45], v[44:45], v[240:241]
	v_pk_mul_f32 v[46:47], v[46:47], v[242:243]
	v_pk_mul_f32 v[16:17], v[16:17], v[228:229]
	v_pk_mul_f32 v[18:19], v[18:19], v[230:231]
	v_pk_mul_f32 v[20:21], v[20:21], v[232:233]
	v_pk_mul_f32 v[22:23], v[22:23], v[234:235]
	v_pk_mul_f32 v[24:25], v[24:25], v[236:237]
	v_pk_mul_f32 v[26:27], v[26:27], v[238:239]
	v_pk_mul_f32 v[28:29], v[28:29], v[240:241]
	v_pk_mul_f32 v[30:31], v[30:31], v[242:243]

; __device__ __forceinline__ void partialSM(f32x16& p0, f32x16& p1, float& m_reg, float& mn, float& alpha) {
;     ...
;   for (int r = 0; r < 16; ++r) p0[r] = __builtin_amdgcn_exp2f(p0[r]);
; }
; __device__ __forceinline__ void finishSM(f32x16& p0, f32x16& p1, float alpha, float& l_reg, bf16x8& pa0, bf16x8& pa1, bf16x8& pa2, bf16x8& pa3) {
; #pragma unroll
;   for (int r = 0; r < 16; ++r) p1[r] = __builtin_amdgcn_exp2f(p1[r]);
;   float ps = 0;
; #pragma unroll
;   for (int r = 0; r < 16; ++r) ps += p0[r];
; #pragma unroll
;   for (int r = 0; r < 16; ++r) ps += p1[r];
;   { auto rr = __builtin_amdgcn_permlane32_swap(__float_as_uint(ps), __float_as_uint(ps), false, false);
;     ps = __uint_as_float(rr[0]) + __uint_as_float(rr[1]); }
;   l_reg = l_reg * alpha + ps;
;     ...
;   PK4(p0, 0, pa0); PK4(p0, 8, pa1); PK4(p1, 0, pa2); PK4(p1, 8, pa3);
;     ...
; }
; __device__ __forceinline__ void qkt(f32x16& p0, f32x16& p1, const bf16_t* Ks, const bf16x8* qr, int r32, int hi) {
;   p0 = f32x16{}; p1 = f32x16{};
; #pragma unroll
;   for (int d0 = 0; d0 < 8; ++d0) { int cb = (d0 * 16 + hi * 8) * 2;
;     bf16x8 b0 = *reinterpret_cast<const bf16x8*>((const char*)Ks + KSWZ(r32, cb));
;     bf16x8 b1 = *reinterpret_cast<const bf16x8*>((const char*)Ks + KSWZ(32 + r32, cb));
;     p0 = __builtin_amdgcn_mfma_f32_32x32x16_bf16(b0, qr[d0], p0, 0, 0, 0);
;     p1 = __builtin_amdgcn_mfma_f32_32x32x16_bf16(b1, qr[d0], p1, 0, 0, 0); }
.Lda_noresc_0:
	v_exp_f32_e32 v80, v80
	v_exp_f32_e32 v81, v81
	v_exp_f32_e32 v82, v82
	v_exp_f32_e32 v83, v83
	v_exp_f32_e32 v84, v84
	v_exp_f32_e32 v85, v85
	v_exp_f32_e32 v86, v86
	v_exp_f32_e32 v87, v87
	v_exp_f32_e32 v88, v88
	v_exp_f32_e32 v89, v89
	v_exp_f32_e32 v90, v90
	v_exp_f32_e32 v91, v91
	v_exp_f32_e32 v92, v92
	v_exp_f32_e32 v93, v93
	v_exp_f32_e32 v94, v94
	v_exp_f32_e32 v95, v95
	v_exp_f32_e32 v64, v64
	v_exp_f32_e32 v65, v65
	v_exp_f32_e32 v66, v66
	v_exp_f32_e32 v67, v67
	v_exp_f32_e32 v68, v68
	v_exp_f32_e32 v69, v69
	v_exp_f32_e32 v70, v70
	v_exp_f32_e32 v71, v71
	v_exp_f32_e32 v72, v72
	v_exp_f32_e32 v73, v73
	v_exp_f32_e32 v74, v74
	v_exp_f32_e32 v75, v75
	v_exp_f32_e32 v76, v76
	v_exp_f32_e32 v77, v77
	v_exp_f32_e32 v78, v78
	v_exp_f32_e32 v79, v79
	v_add_f32_e32 v190, v80, v81
	v_add_f32_e32 v191, v82, v83
	v_add_f32_e32 v190, v190, v84
	v_add_f32_e32 v191, v191, v85
	v_add_f32_e32 v190, v190, v86
	v_add_f32_e32 v191, v191, v87
	v_add_f32_e32 v190, v190, v88
	v_add_f32_e32 v191, v191, v89
	v_add_f32_e32 v190, v190, v90
	v_add_f32_e32 v191, v191, v91
	v_add_f32_e32 v190, v190, v92
	v_add_f32_e32 v191, v191, v93
	v_add_f32_e32 v190, v190, v94
	v_add_f32_e32 v191, v191, v95
	v_add_f32_e32 v190, v190, v64
	v_add_f32_e32 v191, v191, v65
	v_add_f32_e32 v190, v190, v66
	v_add_f32_e32 v191, v191, v67
	v_add_f32_e32 v190, v190, v68
	v_add_f32_e32 v191, v191, v69
	v_add_f32_e32 v190, v190, v70
	v_add_f32_e32 v191, v191, v71
	v_add_f32_e32 v190, v190, v72
	v_add_f32_e32 v191, v191, v73
	v_add_f32_e32 v190, v190, v74
	v_add_f32_e32 v191, v191, v75
	v_add_f32_e32 v190, v190, v76
	v_add_f32_e32 v191, v191, v77
	v_add_f32_e32 v190, v190, v78
	v_add_f32_e32 v191, v191, v79
	v_add_f32_e32 v190, v190, v191
	v_cvt_pk_bf16_f32 v166, v80, v81
	v_cvt_pk_bf16_f32 v167, v82, v83
	v_cvt_pk_bf16_f32 v168, v84, v85
	v_cvt_pk_bf16_f32 v169, v86, v87
	v_cvt_pk_bf16_f32 v170, v88, v89
	v_cvt_pk_bf16_f32 v171, v90, v91
	v_cvt_pk_bf16_f32 v172, v92, v93
	v_cvt_pk_bf16_f32 v173, v94, v95
	v_cvt_pk_bf16_f32 v176, v64, v65
	v_cvt_pk_bf16_f32 v177, v66, v67
	v_cvt_pk_bf16_f32 v178, v68, v69
	v_cvt_pk_bf16_f32 v179, v70, v71
	v_cvt_pk_bf16_f32 v180, v72, v73
	v_cvt_pk_bf16_f32 v181, v74, v75
	v_cvt_pk_bf16_f32 v182, v76, v77
	v_cvt_pk_bf16_f32 v183, v78, v79
	s_nop 1
	v_permlane32_swap_b32_e32 v166, v168
	v_permlane32_swap_b32_e32 v167, v169
	v_permlane32_swap_b32_e32 v170, v172
	v_permlane32_swap_b32_e32 v171, v173
	v_permlane32_swap_b32_e32 v176, v178
	v_permlane32_swap_b32_e32 v177, v179
	v_permlane32_swap_b32_e32 v180, v182
	v_permlane32_swap_b32_e32 v181, v183
	v_add_f32_e32 v175, v175, v190
	s_add_u32 s31, s31, 1
	s_cmp_lt_u32 s31, 132
	s_cbranch_scc0 .Lda_skipk_0
	ds_read_b128 v[150:153], v204 offset:16384
	ds_read_b128 v[154:157], v204 offset:24576
	ds_read_b128 v[158:161], v205 offset:16384
	ds_read_b128 v[162:165], v205 offset:24576
	ds_read_b128 v[228:231], v206 offset:16384
	ds_read_b128 v[232:235], v206 offset:24576
	ds_read_b128 v[236:239], v207 offset:16384
	ds_read_b128 v[240:243], v207 offset:24576
.Lda_skipk_0:
	s_barrier
	s_setprio 3
	s_waitcnt vmcnt(4)
	ds_write_b128 v197, v[186:189] offset:49152
	ds_write_b128 v197, v[220:223] offset:57344
	ds_write_b128 v185, v[246:249] offset:49152
	ds_write_b128 v185, v[200:203] offset:57344
	s_waitcnt lgkmcnt(10)
	v_mfma_f32_32x32x16_bf16 v[80:95], v[150:153], v[130:133], 0
	v_mfma_f32_32x32x16_bf16 v[64:79], v[154:157], v[130:133], 0
	global_load_dwordx4 v[186:189], v184, s[16:17]
	global_load_dwordx4 v[220:223], v184, s[2:3]
	global_load_dwordx4 v[246:249], v184, s[14:15]
	global_load_dwordx4 v[200:203], v184, s[10:11]
	s_add_u32 s16, s16, 0x60000
	s_addc_u32 s17, s17, 0
	s_add_u32 s2, s2, 0x60000
	s_addc_u32 s3, s3, 0
	s_add_u32 s14, s14, 0x60000
	s_addc_u32 s15, s15, 0
	s_add_u32 s10, s10, 0x60000
	s_addc_u32 s11, s11, 0
	ds_read_b128 v[150:153], v208 offset:16384
	ds_read_b128 v[154:157], v208 offset:24576
	s_waitcnt lgkmcnt(10)
	v_mfma_f32_32x32x16_bf16 v[80:95], v[158:161], v[126:129], v[80:95]
	v_mfma_f32_32x32x16_bf16 v[64:79], v[162:165], v[126:129], v[64:79]
	ds_read_b128 v[158:161], v209 offset:16384
	ds_read_b128 v[162:165], v209 offset:24576
	s_waitcnt lgkmcnt(10)
	v_mfma_f32_32x32x16_bf16 v[80:95], v[228:231], v[122:125], v[80:95]
	v_mfma_f32_32x32x16_bf16 v[64:79], v[232:235], v[122:125], v[64:79]
	ds_read_b128 v[228:231], v210 offset:16384
	ds_read_b128 v[232:235], v210 offset:24576
	s_waitcnt lgkmcnt(10)
	v_mfma_f32_32x32x16_bf16 v[80:95], v[236:239], v[118:121], v[80:95]
	v_mfma_f32_32x32x16_bf16 v[64:79], v[240:243], v[118:121], v[64:79]
	ds_read_b128 v[236:239], v211 offset:16384
	ds_read_b128 v[240:243], v211 offset:24576
	s_waitcnt lgkmcnt(6)
	v_mfma_f32_32x32x16_bf16 v[80:95], v[150:153], v[114:117], v[80:95]
	v_mfma_f32_32x32x16_bf16 v[64:79], v[154:157], v[114:117], v[64:79]
	ds_read_b64_tr_b16 v[150:151], v196 offset:0
	ds_read_b64_tr_b16 v[152:153], v196 offset:2048
	ds_read_b64_tr_b16 v[154:155], v196 offset:4096
	ds_read_b64_tr_b16 v[156:157], v196 offset:6144
	s_waitcnt lgkmcnt(8)
	v_mfma_f32_32x32x16_bf16 v[80:95], v[158:161], v[110:113], v[80:95]
	v_mfma_f32_32x32x16_bf16 v[64:79], v[162:165], v[110:113], v[64:79]
	ds_read_b64_tr_b16 v[158:159], v196 offset:8192
	ds_read_b64_tr_b16 v[160:161], v196 offset:10240
	ds_read_b64_tr_b16 v[162:163], v196 offset:12288
	ds_read_b64_tr_b16 v[164:165], v196 offset:14336
	s_waitcnt lgkmcnt(10)
; #define SBAR() __builtin_amdgcn_sched_barrier(0)
; __device__ __forceinline__ void partialSM(f32x16& p0, f32x16& p1, float& m_reg, float& mn, float& alpha) {
;   constexpr float C = SCALE * 1.4426950408889634f;
;   float pmax = p0[0];
; #pragma unroll
;   for (int r = 1; r < 16; ++r) pmax = fmaxf(pmax, p0[r]);
; #pragma unroll
;   for (int r = 0; r < 16; ++r) pmax = fmaxf(pmax, p1[r]);
;   { auto rr = __builtin_amdgcn_permlane32_swap(__float_as_uint(pmax), __float_as_uint(pmax), false, false);
;     pmax = fmaxf(__uint_as_float(rr[0]), __uint_as_float(rr[1])); }
;   if (__builtin_expect(__all(pmax - m_reg <= THR / SCALE), 1)) { mn = m_reg; alpha = 1.f; }
;   else { mn = fmaxf(m_reg, pmax); alpha = __builtin_amdgcn_exp2f((m_reg - mn) * C); m_reg = mn; }
; template <int D0> __device__ __forceinline__ void pv_one(f32x16& od, int vb, bf16x8 pa0, bf16x8 pa1, bf16x8 pa2, bf16x8 pa3) {
;   const s16x4 l0 = tr_read<v_rd_off(D0, 0, 0)>(vb), h0 = tr_read<v_rd_off(D0, 0, 1)>(vb), l1 = tr_read<v_rd_off(D0, 1, 0)>(vb), h1 = tr_read<v_rd_off(D0, 1, 1)>(vb);
;   const s16x4 l2 = tr_read<v_rd_off(D0, 2, 0)>(vb), h2 = tr_read<v_rd_off(D0, 2, 1)>(vb), l3 = tr_read<v_rd_off(D0, 3, 0)>(vb), h3 = tr_read<v_rd_off(D0, 3, 1)>(vb);
;   asm volatile("s_waitcnt lgkmcnt(0)" ::: "memory"); SBAR();
;     ...
;   od = __builtin_amdgcn_mfma_f32_32x32x16_bf16(pa0, PK(l0, h0), od, 0, 0, 0);
;   od = __builtin_amdgcn_mfma_f32_32x32x16_bf16(pa1, PK(l1, h1), od, 0, 0, 0);
;   od = __builtin_amdgcn_mfma_f32_32x32x16_bf16(pa2, PK(l2, h2), od, 0, 0, 0);
;   od = __builtin_amdgcn_mfma_f32_32x32x16_bf16(pa3, PK(l3, h3), od, 0, 0, 0);
;     ...
; }
	v_mfma_f32_32x32x16_bf16 v[80:95], v[228:231], v[106:109], v[80:95]
	v_mfma_f32_32x32x16_bf16 v[64:79], v[232:235], v[106:109], v[64:79]
	ds_read_b64_tr_b16 v[228:229], v196 offset:512
	ds_read_b64_tr_b16 v[230:231], v196 offset:2560
	ds_read_b64_tr_b16 v[232:233], v196 offset:4608
	ds_read_b64_tr_b16 v[234:235], v196 offset:6656
	s_waitcnt lgkmcnt(12)
	v_mfma_f32_32x32x16_bf16 v[80:95], v[236:239], v[102:105], v[80:95]
	v_mfma_f32_32x32x16_bf16 v[64:79], v[240:243], v[102:105], v[64:79]
	ds_read_b64_tr_b16 v[236:237], v196 offset:8704
	ds_read_b64_tr_b16 v[238:239], v196 offset:10752
	s_waitcnt lgkmcnt(12)
	v_mfma_f32_32x32x16_bf16 v[0:15], v[166:169], v[150:153], v[0:15]
	ds_read_b64_tr_b16 v[240:241], v196 offset:12800
	ds_read_b64_tr_b16 v[242:243], v196 offset:14848
	s_waitcnt lgkmcnt(12)
	v_mfma_f32_32x32x16_bf16 v[0:15], v[170:173], v[154:157], v[0:15]
	ds_read_b64_tr_b16 v[150:151], v196 offset:1024
	ds_read_b64_tr_b16 v[152:153], v196 offset:3072
	s_waitcnt lgkmcnt(12)
	v_mfma_f32_32x32x16_bf16 v[0:15], v[176:179], v[158:161], v[0:15]
	ds_read_b64_tr_b16 v[154:155], v196 offset:5120
	ds_read_b64_tr_b16 v[156:157], v196 offset:7168
	s_waitcnt lgkmcnt(12)
	v_mfma_f32_32x32x16_bf16 v[0:15], v[180:183], v[162:165], v[0:15]
	ds_read_b64_tr_b16 v[158:159], v196 offset:9216
	ds_read_b64_tr_b16 v[160:161], v196 offset:11264
	s_waitcnt lgkmcnt(12)
	v_mfma_f32_32x32x16_bf16 v[48:63], v[166:169], v[228:231], v[48:63]
	ds_read_b64_tr_b16 v[162:163], v196 offset:13312
	ds_read_b64_tr_b16 v[164:165], v196 offset:15360
	s_waitcnt lgkmcnt(12)
	v_mfma_f32_32x32x16_bf16 v[48:63], v[170:173], v[232:235], v[48:63]
	ds_read_b64_tr_b16 v[228:229], v196 offset:1536
	ds_read_b64_tr_b16 v[230:231], v196 offset:3584
	s_waitcnt lgkmcnt(12)
	v_mfma_f32_32x32x16_bf16 v[48:63], v[176:179], v[236:239], v[48:63]
	ds_read_b64_tr_b16 v[232:233], v196 offset:5632
	ds_read_b64_tr_b16 v[234:235], v196 offset:7680
	s_waitcnt lgkmcnt(12)
	v_mfma_f32_32x32x16_bf16 v[48:63], v[180:183], v[240:243], v[48:63]
	ds_read_b64_tr_b16 v[236:237], v196 offset:9728
	ds_read_b64_tr_b16 v[238:239], v196 offset:11776
	s_waitcnt lgkmcnt(12)
	v_mfma_f32_32x32x16_bf16 v[32:47], v[166:169], v[150:153], v[32:47]
	ds_read_b64_tr_b16 v[240:241], v196 offset:13824
	ds_read_b64_tr_b16 v[242:243], v196 offset:15872
	s_waitcnt lgkmcnt(12)
	v_mfma_f32_32x32x16_bf16 v[32:47], v[170:173], v[154:157], v[32:47]
	s_waitcnt lgkmcnt(10)
	v_mfma_f32_32x32x16_bf16 v[32:47], v[176:179], v[158:161], v[32:47]
	s_waitcnt lgkmcnt(8)
	v_mfma_f32_32x32x16_bf16 v[32:47], v[180:183], v[162:165], v[32:47]
	s_waitcnt lgkmcnt(6)
	v_mfma_f32_32x32x16_bf16 v[16:31], v[166:169], v[228:231], v[16:31]
	s_waitcnt lgkmcnt(4)
	v_mfma_f32_32x32x16_bf16 v[16:31], v[170:173], v[232:235], v[16:31]
	s_waitcnt lgkmcnt(2)
	v_mfma_f32_32x32x16_bf16 v[16:31], v[176:179], v[236:239], v[16:31]
	s_waitcnt lgkmcnt(0)
	v_mfma_f32_32x32x16_bf16 v[16:31], v[180:183], v[240:243], v[16:31]
	s_setprio 0
	s_barrier
	v_max3_f32 v190, v80, v81, v82
	v_max3_f32 v191, v64, v65, v66
	v_max3_f32 v190, v190, v83, v84
	v_max3_f32 v191, v191, v67, v68
	v_max3_f32 v190, v190, v85, v86
	v_max3_f32 v191, v191, v69, v70
	v_max3_f32 v190, v190, v87, v88
	v_max3_f32 v191, v191, v71, v72
	v_max3_f32 v190, v190, v89, v90
	v_max3_f32 v191, v191, v73, v74
	v_max3_f32 v190, v190, v91, v92
	v_max3_f32 v191, v191, v75, v76
	v_max3_f32 v190, v190, v93, v94
	v_max3_f32 v191, v191, v77, v78
	v_max3_f32 v190, v190, v95, v79
	v_max_f32_e32 v190, v190, v191
	v_sub_f32_e32 v215, v190, v174
	v_cmp_ge_f32_e32 vcc, s86, v215
	s_nop 3
	s_cmp_eq_u64 vcc, exec
	s_cbranch_scc1 .Lda_common_1
	v_mov_b32_e32 v191, v190
	s_nop 1
	v_permlane32_swap_b32_e32 v190, v191
	s_nop 0
	v_max_f32_e32 v212, v190, v191
	v_max_f32_e32 v191, v174, v212
	v_sub_f32_e32 v215, v174, v191
	v_mul_f32_e32 v215, s92, v215
	v_exp_f32_e32 v213, v215
	v_mov_b32_e32 v174, v191
	v_mul_f32_e32 v214, 0xbe0293ee, v174
	v_mul_f32_e32 v175, v175, v213
	s_and_saveexec_b64 s[12:13], s[40:41]
	ds_write_b32 v199, v213 offset:128
	s_or_b64 exec, exec, s[12:13]
	s_waitcnt lgkmcnt(0)
	v_add_u32_e32 v215, v99, v96
	ds_read_b128 v[228:231], v215 offset:128
	ds_read_b128 v[232:235], v215 offset:160
	ds_read_b128 v[236:239], v215 offset:192
	ds_read_b128 v[240:243], v215 offset:224
	s_waitcnt lgkmcnt(0)
	v_pk_mul_f32 v[0:1], v[0:1], v[228:229]
	v_pk_mul_f32 v[2:3], v[2:3], v[230:231]
	v_pk_mul_f32 v[4:5], v[4:5], v[232:233]
	v_pk_mul_f32 v[6:7], v[6:7], v[234:235]
	v_pk_mul_f32 v[8:9], v[8:9], v[236:237]
	v_pk_mul_f32 v[10:11], v[10:11], v[238:239]
	v_pk_mul_f32 v[12:13], v[12:13], v[240:241]
	v_pk_mul_f32 v[14:15], v[14:15], v[242:243]
	v_pk_mul_f32 v[48:49], v[48:49], v[228:229]
	v_pk_mul_f32 v[50:51], v[50:51], v[230:231]
	v_pk_mul_f32 v[52:53], v[52:53], v[232:233]
	v_pk_mul_f32 v[54:55], v[54:55], v[234:235]
	v_pk_mul_f32 v[56:57], v[56:57], v[236:237]
	v_pk_mul_f32 v[58:59], v[58:59], v[238:239]
	v_pk_mul_f32 v[60:61], v[60:61], v[240:241]
	v_pk_mul_f32 v[62:63], v[62:63], v[242:243]
	v_pk_mul_f32 v[32:33], v[32:33], v[228:229]
	v_pk_mul_f32 v[34:35], v[34:35], v[230:231]
	v_pk_mul_f32 v[36:37], v[36:37], v[232:233]
	v_pk_mul_f32 v[38:39], v[38:39], v[234:235]
	v_pk_mul_f32 v[40:41], v[40:41], v[236:237]
	v_pk_mul_f32 v[42:43], v[42:43], v[238:239]
	v_pk_mul_f32 v[44:45], v[44:45], v[240:241]
	v_pk_mul_f32 v[46:47], v[46:47], v[242:243]
	v_pk_mul_f32 v[16:17], v[16:17], v[228:229]
	v_pk_mul_f32 v[18:19], v[18:19], v[230:231]
	v_pk_mul_f32 v[20:21], v[20:21], v[232:233]
	v_pk_mul_f32 v[22:23], v[22:23], v[234:235]
	v_pk_mul_f32 v[24:25], v[24:25], v[236:237]
	v_pk_mul_f32 v[26:27], v[26:27], v[238:239]
	v_pk_mul_f32 v[28:29], v[28:29], v[240:241]
	v_pk_mul_f32 v[30:31], v[30:31], v[242:243]

; __device__ __forceinline__ void partialSM(f32x16& p0, f32x16& p1, float& m_reg, float& mn, float& alpha) {
;     ...
;   for (int r = 0; r < 16; ++r) p0[r] = __builtin_amdgcn_exp2f(p0[r]);
; }
; __device__ __forceinline__ void finishSM(f32x16& p0, f32x16& p1, float alpha, float& l_reg, bf16x8& pa0, bf16x8& pa1, bf16x8& pa2, bf16x8& pa3) {
; #pragma unroll
;   for (int r = 0; r < 16; ++r) p1[r] = __builtin_amdgcn_exp2f(p1[r]);
;   float ps = 0;
; #pragma unroll
;   for (int r = 0; r < 16; ++r) ps += p0[r];
; #pragma unroll
;   for (int r = 0; r < 16; ++r) ps += p1[r];
;   { auto rr = __builtin_amdgcn_permlane32_swap(__float_as_uint(ps), __float_as_uint(ps), false, false);
;     ps = __uint_as_float(rr[0]) + __uint_as_float(rr[1]); }
;   l_reg = l_reg * alpha + ps;
;     ...
;   PK4(p0, 0, pa0); PK4(p0, 8, pa1); PK4(p1, 0, pa2); PK4(p1, 8, pa3);
;     ...
; }
; __device__ __forceinline__ void qkt(f32x16& p0, f32x16& p1, const bf16_t* Ks, const bf16x8* qr, int r32, int hi) {
;   p0 = f32x16{}; p1 = f32x16{};
; #pragma unroll
;   for (int d0 = 0; d0 < 8; ++d0) { int cb = (d0 * 16 + hi * 8) * 2;
;     bf16x8 b0 = *reinterpret_cast<const bf16x8*>((const char*)Ks + KSWZ(r32, cb));
;     bf16x8 b1 = *reinterpret_cast<const bf16x8*>((const char*)Ks + KSWZ(32 + r32, cb));
;     p0 = __builtin_amdgcn_mfma_f32_32x32x16_bf16(b0, qr[d0], p0, 0, 0, 0);
;     p1 = __builtin_amdgcn_mfma_f32_32x32x16_bf16(b1, qr[d0], p1, 0, 0, 0); }
.Lda_noresc_1:
	v_exp_f32_e32 v80, v80
	v_exp_f32_e32 v81, v81
	v_exp_f32_e32 v82, v82
	v_exp_f32_e32 v83, v83
	v_exp_f32_e32 v84, v84
	v_exp_f32_e32 v85, v85
	v_exp_f32_e32 v86, v86
	v_exp_f32_e32 v87, v87
	v_exp_f32_e32 v88, v88
	v_exp_f32_e32 v89, v89
	v_exp_f32_e32 v90, v90
	v_exp_f32_e32 v91, v91
	v_exp_f32_e32 v92, v92
	v_exp_f32_e32 v93, v93
	v_exp_f32_e32 v94, v94
	v_exp_f32_e32 v95, v95
	v_exp_f32_e32 v64, v64
	v_exp_f32_e32 v65, v65
	v_exp_f32_e32 v66, v66
	v_exp_f32_e32 v67, v67
	v_exp_f32_e32 v68, v68
	v_exp_f32_e32 v69, v69
	v_exp_f32_e32 v70, v70
	v_exp_f32_e32 v71, v71
	v_exp_f32_e32 v72, v72
	v_exp_f32_e32 v73, v73
	v_exp_f32_e32 v74, v74
	v_exp_f32_e32 v75, v75
	v_exp_f32_e32 v76, v76
	v_exp_f32_e32 v77, v77
	v_exp_f32_e32 v78, v78
	v_exp_f32_e32 v79, v79
	v_add_f32_e32 v190, v80, v81
	v_add_f32_e32 v191, v82, v83
	v_add_f32_e32 v190, v190, v84
	v_add_f32_e32 v191, v191, v85
	v_add_f32_e32 v190, v190, v86
	v_add_f32_e32 v191, v191, v87
	v_add_f32_e32 v190, v190, v88
	v_add_f32_e32 v191, v191, v89
	v_add_f32_e32 v190, v190, v90
	v_add_f32_e32 v191, v191, v91
	v_add_f32_e32 v190, v190, v92
	v_add_f32_e32 v191, v191, v93
	v_add_f32_e32 v190, v190, v94
	v_add_f32_e32 v191, v191, v95
	v_add_f32_e32 v190, v190, v64
	v_add_f32_e32 v191, v191, v65
	v_add_f32_e32 v190, v190, v66
	v_add_f32_e32 v191, v191, v67
	v_add_f32_e32 v190, v190, v68
	v_add_f32_e32 v191, v191, v69
	v_add_f32_e32 v190, v190, v70
	v_add_f32_e32 v191, v191, v71
	v_add_f32_e32 v190, v190, v72
	v_add_f32_e32 v191, v191, v73
	v_add_f32_e32 v190, v190, v74
	v_add_f32_e32 v191, v191, v75
	v_add_f32_e32 v190, v190, v76
	v_add_f32_e32 v191, v191, v77
	v_add_f32_e32 v190, v190, v78
	v_add_f32_e32 v191, v191, v79
	v_add_f32_e32 v190, v190, v191
	v_cvt_pk_bf16_f32 v166, v80, v81
	v_cvt_pk_bf16_f32 v167, v82, v83
	v_cvt_pk_bf16_f32 v168, v84, v85
	v_cvt_pk_bf16_f32 v169, v86, v87
	v_cvt_pk_bf16_f32 v170, v88, v89
	v_cvt_pk_bf16_f32 v171, v90, v91
	v_cvt_pk_bf16_f32 v172, v92, v93
	v_cvt_pk_bf16_f32 v173, v94, v95
	v_cvt_pk_bf16_f32 v176, v64, v65
	v_cvt_pk_bf16_f32 v177, v66, v67
	v_cvt_pk_bf16_f32 v178, v68, v69
	v_cvt_pk_bf16_f32 v179, v70, v71
	v_cvt_pk_bf16_f32 v180, v72, v73
	v_cvt_pk_bf16_f32 v181, v74, v75
	v_cvt_pk_bf16_f32 v182, v76, v77
	v_cvt_pk_bf16_f32 v183, v78, v79
	s_nop 1
	v_permlane32_swap_b32_e32 v166, v168
	v_permlane32_swap_b32_e32 v167, v169
	v_permlane32_swap_b32_e32 v170, v172
	v_permlane32_swap_b32_e32 v171, v173
	v_permlane32_swap_b32_e32 v176, v178
	v_permlane32_swap_b32_e32 v177, v179
	v_permlane32_swap_b32_e32 v180, v182
	v_permlane32_swap_b32_e32 v181, v183
	v_add_f32_e32 v175, v175, v190
	s_add_u32 s31, s31, 1
	s_cmp_lt_u32 s31, 132
	s_cbranch_scc0 .Lda_skipk_1
	ds_read_b128 v[150:153], v204 offset:32768
	ds_read_b128 v[154:157], v204 offset:40960
	ds_read_b128 v[158:161], v205 offset:32768
	ds_read_b128 v[162:165], v205 offset:40960
	ds_read_b128 v[228:231], v206 offset:32768
	ds_read_b128 v[232:235], v206 offset:40960
	ds_read_b128 v[236:239], v207 offset:32768
	ds_read_b128 v[240:243], v207 offset:40960
.Lda_skipk_1:
	s_barrier
	s_setprio 3
	s_waitcnt vmcnt(4)
	ds_write_b128 v197, v[134:137] offset:0
	ds_write_b128 v197, v[138:141] offset:8192
	ds_write_b128 v185, v[142:145] offset:0
	ds_write_b128 v185, v[146:149] offset:8192
	s_waitcnt lgkmcnt(10)
	v_mfma_f32_32x32x16_bf16 v[80:95], v[150:153], v[130:133], 0
	v_mfma_f32_32x32x16_bf16 v[64:79], v[154:157], v[130:133], 0
	global_load_dwordx4 v[134:137], v184, s[16:17]
	global_load_dwordx4 v[138:141], v184, s[2:3]
	global_load_dwordx4 v[142:145], v184, s[14:15]
	global_load_dwordx4 v[146:149], v184, s[10:11]
	s_add_u32 s16, s16, 0x60000
	s_addc_u32 s17, s17, 0
	s_add_u32 s2, s2, 0x60000
	s_addc_u32 s3, s3, 0
	s_add_u32 s14, s14, 0x60000
	s_addc_u32 s15, s15, 0
	s_add_u32 s10, s10, 0x60000
	s_addc_u32 s11, s11, 0
	ds_read_b128 v[150:153], v208 offset:32768
	ds_read_b128 v[154:157], v208 offset:40960
	s_waitcnt lgkmcnt(10)
	v_mfma_f32_32x32x16_bf16 v[80:95], v[158:161], v[126:129], v[80:95]
	v_mfma_f32_32x32x16_bf16 v[64:79], v[162:165], v[126:129], v[64:79]
	ds_read_b128 v[158:161], v209 offset:32768
	ds_read_b128 v[162:165], v209 offset:40960
	s_waitcnt lgkmcnt(10)
	v_mfma_f32_32x32x16_bf16 v[80:95], v[228:231], v[122:125], v[80:95]
	v_mfma_f32_32x32x16_bf16 v[64:79], v[232:235], v[122:125], v[64:79]
	ds_read_b128 v[228:231], v210 offset:32768
	ds_read_b128 v[232:235], v210 offset:40960
	s_waitcnt lgkmcnt(10)
	v_mfma_f32_32x32x16_bf16 v[80:95], v[236:239], v[118:121], v[80:95]
	v_mfma_f32_32x32x16_bf16 v[64:79], v[240:243], v[118:121], v[64:79]
	ds_read_b128 v[236:239], v211 offset:32768
	ds_read_b128 v[240:243], v211 offset:40960
	s_waitcnt lgkmcnt(6)
	v_mfma_f32_32x32x16_bf16 v[80:95], v[150:153], v[114:117], v[80:95]
	v_mfma_f32_32x32x16_bf16 v[64:79], v[154:157], v[114:117], v[64:79]
	ds_read_b64_tr_b16 v[150:151], v196 offset:16384
	ds_read_b64_tr_b16 v[152:153], v196 offset:18432
	ds_read_b64_tr_b16 v[154:155], v196 offset:20480
	ds_read_b64_tr_b16 v[156:157], v196 offset:22528
	s_waitcnt lgkmcnt(8)
	v_mfma_f32_32x32x16_bf16 v[80:95], v[158:161], v[110:113], v[80:95]
	v_mfma_f32_32x32x16_bf16 v[64:79], v[162:165], v[110:113], v[64:79]
	ds_read_b64_tr_b16 v[158:159], v196 offset:24576
	ds_read_b64_tr_b16 v[160:161], v196 offset:26624
	ds_read_b64_tr_b16 v[162:163], v196 offset:28672
	ds_read_b64_tr_b16 v[164:165], v196 offset:30720
	s_waitcnt lgkmcnt(10)
; #define SBAR() __builtin_amdgcn_sched_barrier(0)
; __device__ __forceinline__ void partialSM(f32x16& p0, f32x16& p1, float& m_reg, float& mn, float& alpha) {
;   constexpr float C = SCALE * 1.4426950408889634f;
;   float pmax = p0[0];
; #pragma unroll
;   for (int r = 1; r < 16; ++r) pmax = fmaxf(pmax, p0[r]);
; #pragma unroll
;   for (int r = 0; r < 16; ++r) pmax = fmaxf(pmax, p1[r]);
;   { auto rr = __builtin_amdgcn_permlane32_swap(__float_as_uint(pmax), __float_as_uint(pmax), false, false);
;     pmax = fmaxf(__uint_as_float(rr[0]), __uint_as_float(rr[1])); }
;   if (__builtin_expect(__all(pmax - m_reg <= THR / SCALE), 1)) { mn = m_reg; alpha = 1.f; }
;   else { mn = fmaxf(m_reg, pmax); alpha = __builtin_amdgcn_exp2f((m_reg - mn) * C); m_reg = mn; }
; template <int D0> __device__ __forceinline__ void pv_one(f32x16& od, int vb, bf16x8 pa0, bf16x8 pa1, bf16x8 pa2, bf16x8 pa3) {
;   const s16x4 l0 = tr_read<v_rd_off(D0, 0, 0)>(vb), h0 = tr_read<v_rd_off(D0, 0, 1)>(vb), l1 = tr_read<v_rd_off(D0, 1, 0)>(vb), h1 = tr_read<v_rd_off(D0, 1, 1)>(vb);
;   const s16x4 l2 = tr_read<v_rd_off(D0, 2, 0)>(vb), h2 = tr_read<v_rd_off(D0, 2, 1)>(vb), l3 = tr_read<v_rd_off(D0, 3, 0)>(vb), h3 = tr_read<v_rd_off(D0, 3, 1)>(vb);
;   asm volatile("s_waitcnt lgkmcnt(0)" ::: "memory"); SBAR();
;     ...
;   od = __builtin_amdgcn_mfma_f32_32x32x16_bf16(pa0, PK(l0, h0), od, 0, 0, 0);
;   od = __builtin_amdgcn_mfma_f32_32x32x16_bf16(pa1, PK(l1, h1), od, 0, 0, 0);
;   od = __builtin_amdgcn_mfma_f32_32x32x16_bf16(pa2, PK(l2, h2), od, 0, 0, 0);
;   od = __builtin_amdgcn_mfma_f32_32x32x16_bf16(pa3, PK(l3, h3), od, 0, 0, 0);
;     ...
; }
	v_mfma_f32_32x32x16_bf16 v[80:95], v[228:231], v[106:109], v[80:95]
	v_mfma_f32_32x32x16_bf16 v[64:79], v[232:235], v[106:109], v[64:79]
	ds_read_b64_tr_b16 v[228:229], v196 offset:16896
	ds_read_b64_tr_b16 v[230:231], v196 offset:18944
	ds_read_b64_tr_b16 v[232:233], v196 offset:20992
	ds_read_b64_tr_b16 v[234:235], v196 offset:23040
	s_waitcnt lgkmcnt(12)
	v_mfma_f32_32x32x16_bf16 v[80:95], v[236:239], v[102:105], v[80:95]
	v_mfma_f32_32x32x16_bf16 v[64:79], v[240:243], v[102:105], v[64:79]
	ds_read_b64_tr_b16 v[236:237], v196 offset:25088
	ds_read_b64_tr_b16 v[238:239], v196 offset:27136
	s_waitcnt lgkmcnt(12)
	v_mfma_f32_32x32x16_bf16 v[0:15], v[166:169], v[150:153], v[0:15]
	ds_read_b64_tr_b16 v[240:241], v196 offset:29184
	ds_read_b64_tr_b16 v[242:243], v196 offset:31232
	s_waitcnt lgkmcnt(12)
	v_mfma_f32_32x32x16_bf16 v[0:15], v[170:173], v[154:157], v[0:15]
	ds_read_b64_tr_b16 v[150:151], v196 offset:17408
	ds_read_b64_tr_b16 v[152:153], v196 offset:19456
	s_waitcnt lgkmcnt(12)
	v_mfma_f32_32x32x16_bf16 v[0:15], v[176:179], v[158:161], v[0:15]
	ds_read_b64_tr_b16 v[154:155], v196 offset:21504
	ds_read_b64_tr_b16 v[156:157], v196 offset:23552
	s_waitcnt lgkmcnt(12)
	v_mfma_f32_32x32x16_bf16 v[0:15], v[180:183], v[162:165], v[0:15]
	ds_read_b64_tr_b16 v[158:159], v196 offset:25600
	ds_read_b64_tr_b16 v[160:161], v196 offset:27648
	s_waitcnt lgkmcnt(12)
	v_mfma_f32_32x32x16_bf16 v[48:63], v[166:169], v[228:231], v[48:63]
	ds_read_b64_tr_b16 v[162:163], v196 offset:29696
	ds_read_b64_tr_b16 v[164:165], v196 offset:31744
	s_waitcnt lgkmcnt(12)
	v_mfma_f32_32x32x16_bf16 v[48:63], v[170:173], v[232:235], v[48:63]
	ds_read_b64_tr_b16 v[228:229], v196 offset:17920
	ds_read_b64_tr_b16 v[230:231], v196 offset:19968
	s_waitcnt lgkmcnt(12)
	v_mfma_f32_32x32x16_bf16 v[48:63], v[176:179], v[236:239], v[48:63]
	ds_read_b64_tr_b16 v[232:233], v196 offset:22016
	ds_read_b64_tr_b16 v[234:235], v196 offset:24064
	s_waitcnt lgkmcnt(12)
	v_mfma_f32_32x32x16_bf16 v[48:63], v[180:183], v[240:243], v[48:63]
	ds_read_b64_tr_b16 v[236:237], v196 offset:26112
	ds_read_b64_tr_b16 v[238:239], v196 offset:28160
	s_waitcnt lgkmcnt(12)
	v_mfma_f32_32x32x16_bf16 v[32:47], v[166:169], v[150:153], v[32:47]
	ds_read_b64_tr_b16 v[240:241], v196 offset:30208
	ds_read_b64_tr_b16 v[242:243], v196 offset:32256
	s_waitcnt lgkmcnt(12)
	v_mfma_f32_32x32x16_bf16 v[32:47], v[170:173], v[154:157], v[32:47]
	s_waitcnt lgkmcnt(10)
	v_mfma_f32_32x32x16_bf16 v[32:47], v[176:179], v[158:161], v[32:47]
	s_waitcnt lgkmcnt(8)
	v_mfma_f32_32x32x16_bf16 v[32:47], v[180:183], v[162:165], v[32:47]
	s_waitcnt lgkmcnt(6)
	v_mfma_f32_32x32x16_bf16 v[16:31], v[166:169], v[228:231], v[16:31]
	s_waitcnt lgkmcnt(4)
	v_mfma_f32_32x32x16_bf16 v[16:31], v[170:173], v[232:235], v[16:31]
	s_waitcnt lgkmcnt(2)
	v_mfma_f32_32x32x16_bf16 v[16:31], v[176:179], v[236:239], v[16:31]
	s_waitcnt lgkmcnt(0)
	v_mfma_f32_32x32x16_bf16 v[16:31], v[180:183], v[240:243], v[16:31]
	s_setprio 0
	s_barrier
	v_max3_f32 v190, v80, v81, v82
	v_max3_f32 v191, v64, v65, v66
	v_max3_f32 v190, v190, v83, v84
	v_max3_f32 v191, v191, v67, v68
	v_max3_f32 v190, v190, v85, v86
	v_max3_f32 v191, v191, v69, v70
	v_max3_f32 v190, v190, v87, v88
	v_max3_f32 v191, v191, v71, v72
	v_max3_f32 v190, v190, v89, v90
	v_max3_f32 v191, v191, v73, v74
	v_max3_f32 v190, v190, v91, v92
	v_max3_f32 v191, v191, v75, v76
	v_max3_f32 v190, v190, v93, v94
	v_max3_f32 v191, v191, v77, v78
	v_max3_f32 v190, v190, v95, v79
	v_max_f32_e32 v190, v190, v191
	v_sub_f32_e32 v215, v190, v174
	v_cmp_ge_f32_e32 vcc, s86, v215
	s_nop 3
	s_cmp_eq_u64 vcc, exec
	s_cbranch_scc1 .Lda_common_2
	v_mov_b32_e32 v191, v190
	s_nop 1
	v_permlane32_swap_b32_e32 v190, v191
	s_nop 0
	v_max_f32_e32 v212, v190, v191
	v_max_f32_e32 v191, v174, v212
	v_sub_f32_e32 v215, v174, v191
	v_mul_f32_e32 v215, s92, v215
	v_exp_f32_e32 v213, v215
	v_mov_b32_e32 v174, v191
	v_mul_f32_e32 v214, 0xbe0293ee, v174
	v_mul_f32_e32 v175, v175, v213
	s_and_saveexec_b64 s[12:13], s[40:41]
	ds_write_b32 v199, v213 offset:128
	s_or_b64 exec, exec, s[12:13]
	s_waitcnt lgkmcnt(0)
	v_add_u32_e32 v215, v99, v96
	ds_read_b128 v[228:231], v215 offset:128
	ds_read_b128 v[232:235], v215 offset:160
	ds_read_b128 v[236:239], v215 offset:192
	ds_read_b128 v[240:243], v215 offset:224
	s_waitcnt lgkmcnt(0)
	v_pk_mul_f32 v[0:1], v[0:1], v[228:229]
	v_pk_mul_f32 v[2:3], v[2:3], v[230:231]
	v_pk_mul_f32 v[4:5], v[4:5], v[232:233]
	v_pk_mul_f32 v[6:7], v[6:7], v[234:235]
	v_pk_mul_f32 v[8:9], v[8:9], v[236:237]
	v_pk_mul_f32 v[10:11], v[10:11], v[238:239]
	v_pk_mul_f32 v[12:13], v[12:13], v[240:241]
	v_pk_mul_f32 v[14:15], v[14:15], v[242:243]
	v_pk_mul_f32 v[48:49], v[48:49], v[228:229]
	v_pk_mul_f32 v[50:51], v[50:51], v[230:231]
	v_pk_mul_f32 v[52:53], v[52:53], v[232:233]
	v_pk_mul_f32 v[54:55], v[54:55], v[234:235]
	v_pk_mul_f32 v[56:57], v[56:57], v[236:237]
	v_pk_mul_f32 v[58:59], v[58:59], v[238:239]
	v_pk_mul_f32 v[60:61], v[60:61], v[240:241]
	v_pk_mul_f32 v[62:63], v[62:63], v[242:243]
	v_pk_mul_f32 v[32:33], v[32:33], v[228:229]
	v_pk_mul_f32 v[34:35], v[34:35], v[230:231]
	v_pk_mul_f32 v[36:37], v[36:37], v[232:233]
	v_pk_mul_f32 v[38:39], v[38:39], v[234:235]
	v_pk_mul_f32 v[40:41], v[40:41], v[236:237]
	v_pk_mul_f32 v[42:43], v[42:43], v[238:239]
	v_pk_mul_f32 v[44:45], v[44:45], v[240:241]
	v_pk_mul_f32 v[46:47], v[46:47], v[242:243]
	v_pk_mul_f32 v[16:17], v[16:17], v[228:229]
	v_pk_mul_f32 v[18:19], v[18:19], v[230:231]
	v_pk_mul_f32 v[20:21], v[20:21], v[232:233]
	v_pk_mul_f32 v[22:23], v[22:23], v[234:235]
	v_pk_mul_f32 v[24:25], v[24:25], v[236:237]
	v_pk_mul_f32 v[26:27], v[26:27], v[238:239]
	v_pk_mul_f32 v[28:29], v[28:29], v[240:241]
	v_pk_mul_f32 v[30:31], v[30:31], v[242:243]

; __device__ __forceinline__ void partialSM(f32x16& p0, f32x16& p1, float& m_reg, float& mn, float& alpha) {
;     ...
;   for (int r = 0; r < 16; ++r) p0[r] = __builtin_amdgcn_exp2f(p0[r]);
; }
; __device__ __forceinline__ void finishSM(f32x16& p0, f32x16& p1, float alpha, float& l_reg, bf16x8& pa0, bf16x8& pa1, bf16x8& pa2, bf16x8& pa3) {
; #pragma unroll
;   for (int r = 0; r < 16; ++r) p1[r] = __builtin_amdgcn_exp2f(p1[r]);
;   float ps = 0;
; #pragma unroll
;   for (int r = 0; r < 16; ++r) ps += p0[r];
; #pragma unroll
;   for (int r = 0; r < 16; ++r) ps += p1[r];
;   { auto rr = __builtin_amdgcn_permlane32_swap(__float_as_uint(ps), __float_as_uint(ps), false, false);
;     ps = __uint_as_float(rr[0]) + __uint_as_float(rr[1]); }
;   l_reg = l_reg * alpha + ps;
;     ...
;   PK4(p0, 0, pa0); PK4(p0, 8, pa1); PK4(p1, 0, pa2); PK4(p1, 8, pa3);
;     ...
; }
; __device__ __forceinline__ void qkt(f32x16& p0, f32x16& p1, const bf16_t* Ks, const bf16x8* qr, int r32, int hi) {
;   p0 = f32x16{}; p1 = f32x16{};
; #pragma unroll
;   for (int d0 = 0; d0 < 8; ++d0) { int cb = (d0 * 16 + hi * 8) * 2;
;     bf16x8 b0 = *reinterpret_cast<const bf16x8*>((const char*)Ks + KSWZ(r32, cb));
;     bf16x8 b1 = *reinterpret_cast<const bf16x8*>((const char*)Ks + KSWZ(32 + r32, cb));
;     p0 = __builtin_amdgcn_mfma_f32_32x32x16_bf16(b0, qr[d0], p0, 0, 0, 0);
;     p1 = __builtin_amdgcn_mfma_f32_32x32x16_bf16(b1, qr[d0], p1, 0, 0, 0); }
.Lda_noresc_2:
	v_exp_f32_e32 v80, v80
	v_exp_f32_e32 v81, v81
	v_exp_f32_e32 v82, v82
	v_exp_f32_e32 v83, v83
	v_exp_f32_e32 v84, v84
	v_exp_f32_e32 v85, v85
	v_exp_f32_e32 v86, v86
	v_exp_f32_e32 v87, v87
	v_exp_f32_e32 v88, v88
	v_exp_f32_e32 v89, v89
	v_exp_f32_e32 v90, v90
	v_exp_f32_e32 v91, v91
	v_exp_f32_e32 v92, v92
	v_exp_f32_e32 v93, v93
	v_exp_f32_e32 v94, v94
	v_exp_f32_e32 v95, v95
	v_exp_f32_e32 v64, v64
	v_exp_f32_e32 v65, v65
	v_exp_f32_e32 v66, v66
	v_exp_f32_e32 v67, v67
	v_exp_f32_e32 v68, v68
	v_exp_f32_e32 v69, v69
	v_exp_f32_e32 v70, v70
	v_exp_f32_e32 v71, v71
	v_exp_f32_e32 v72, v72
	v_exp_f32_e32 v73, v73
	v_exp_f32_e32 v74, v74
	v_exp_f32_e32 v75, v75
	v_exp_f32_e32 v76, v76
	v_exp_f32_e32 v77, v77
	v_exp_f32_e32 v78, v78
	v_exp_f32_e32 v79, v79
	v_add_f32_e32 v190, v80, v81
	v_add_f32_e32 v191, v82, v83
	v_add_f32_e32 v190, v190, v84
	v_add_f32_e32 v191, v191, v85
	v_add_f32_e32 v190, v190, v86
	v_add_f32_e32 v191, v191, v87
	v_add_f32_e32 v190, v190, v88
	v_add_f32_e32 v191, v191, v89
	v_add_f32_e32 v190, v190, v90
	v_add_f32_e32 v191, v191, v91
	v_add_f32_e32 v190, v190, v92
	v_add_f32_e32 v191, v191, v93
	v_add_f32_e32 v190, v190, v94
	v_add_f32_e32 v191, v191, v95
	v_add_f32_e32 v190, v190, v64
	v_add_f32_e32 v191, v191, v65
	v_add_f32_e32 v190, v190, v66
	v_add_f32_e32 v191, v191, v67
	v_add_f32_e32 v190, v190, v68
	v_add_f32_e32 v191, v191, v69
	v_add_f32_e32 v190, v190, v70
	v_add_f32_e32 v191, v191, v71
	v_add_f32_e32 v190, v190, v72
	v_add_f32_e32 v191, v191, v73
	v_add_f32_e32 v190, v190, v74
	v_add_f32_e32 v191, v191, v75
	v_add_f32_e32 v190, v190, v76
	v_add_f32_e32 v191, v191, v77
	v_add_f32_e32 v190, v190, v78
	v_add_f32_e32 v191, v191, v79
	v_add_f32_e32 v190, v190, v191
	v_cvt_pk_bf16_f32 v166, v80, v81
	v_cvt_pk_bf16_f32 v167, v82, v83
	v_cvt_pk_bf16_f32 v168, v84, v85
	v_cvt_pk_bf16_f32 v169, v86, v87
	v_cvt_pk_bf16_f32 v170, v88, v89
	v_cvt_pk_bf16_f32 v171, v90, v91
	v_cvt_pk_bf16_f32 v172, v92, v93
	v_cvt_pk_bf16_f32 v173, v94, v95
	v_cvt_pk_bf16_f32 v176, v64, v65
	v_cvt_pk_bf16_f32 v177, v66, v67
	v_cvt_pk_bf16_f32 v178, v68, v69
	v_cvt_pk_bf16_f32 v179, v70, v71
	v_cvt_pk_bf16_f32 v180, v72, v73
	v_cvt_pk_bf16_f32 v181, v74, v75
	v_cvt_pk_bf16_f32 v182, v76, v77
	v_cvt_pk_bf16_f32 v183, v78, v79
	s_nop 1
	v_permlane32_swap_b32_e32 v166, v168
	v_permlane32_swap_b32_e32 v167, v169
	v_permlane32_swap_b32_e32 v170, v172
	v_permlane32_swap_b32_e32 v171, v173
	v_permlane32_swap_b32_e32 v176, v178
	v_permlane32_swap_b32_e32 v177, v179
	v_permlane32_swap_b32_e32 v180, v182
	v_permlane32_swap_b32_e32 v181, v183
	v_add_f32_e32 v175, v175, v190
	s_add_u32 s31, s31, 1
	s_cmp_lt_u32 s31, 132
	s_cbranch_scc0 .Lda_skipk_2
	ds_read_b128 v[150:153], v204 offset:49152
	ds_read_b128 v[154:157], v204 offset:57344
	ds_read_b128 v[158:161], v205 offset:49152
	ds_read_b128 v[162:165], v205 offset:57344
	ds_read_b128 v[228:231], v206 offset:49152
	ds_read_b128 v[232:235], v206 offset:57344
	ds_read_b128 v[236:239], v207 offset:49152
	ds_read_b128 v[240:243], v207 offset:57344
.Lda_skipk_2:
	s_barrier
	s_setprio 3
	s_waitcnt vmcnt(4)
	ds_write_b128 v197, v[186:189] offset:16384
	ds_write_b128 v197, v[220:223] offset:24576
	ds_write_b128 v185, v[246:249] offset:16384
	ds_write_b128 v185, v[200:203] offset:24576
	s_waitcnt lgkmcnt(10)
	v_mfma_f32_32x32x16_bf16 v[80:95], v[150:153], v[130:133], 0
	v_mfma_f32_32x32x16_bf16 v[64:79], v[154:157], v[130:133], 0
	global_load_dwordx4 v[186:189], v184, s[16:17]
	global_load_dwordx4 v[220:223], v184, s[2:3]
	global_load_dwordx4 v[246:249], v184, s[14:15]
	global_load_dwordx4 v[200:203], v184, s[10:11]
	s_add_u32 s16, s16, 0x60000
	s_addc_u32 s17, s17, 0
	s_add_u32 s2, s2, 0x60000
	s_addc_u32 s3, s3, 0
	s_add_u32 s14, s14, 0x60000
	s_addc_u32 s15, s15, 0
	s_add_u32 s10, s10, 0x60000
	s_addc_u32 s11, s11, 0
	ds_read_b128 v[150:153], v208 offset:49152
	ds_read_b128 v[154:157], v208 offset:57344
	s_waitcnt lgkmcnt(10)
	v_mfma_f32_32x32x16_bf16 v[80:95], v[158:161], v[126:129], v[80:95]
	v_mfma_f32_32x32x16_bf16 v[64:79], v[162:165], v[126:129], v[64:79]
	ds_read_b128 v[158:161], v209 offset:49152
	ds_read_b128 v[162:165], v209 offset:57344
	s_waitcnt lgkmcnt(10)
	v_mfma_f32_32x32x16_bf16 v[80:95], v[228:231], v[122:125], v[80:95]
	v_mfma_f32_32x32x16_bf16 v[64:79], v[232:235], v[122:125], v[64:79]
	ds_read_b128 v[228:231], v210 offset:49152
	ds_read_b128 v[232:235], v210 offset:57344
	s_waitcnt lgkmcnt(10)
	v_mfma_f32_32x32x16_bf16 v[80:95], v[236:239], v[118:121], v[80:95]
	v_mfma_f32_32x32x16_bf16 v[64:79], v[240:243], v[118:121], v[64:79]
	ds_read_b128 v[236:239], v211 offset:49152
	ds_read_b128 v[240:243], v211 offset:57344
	s_waitcnt lgkmcnt(6)
	v_mfma_f32_32x32x16_bf16 v[80:95], v[150:153], v[114:117], v[80:95]
	v_mfma_f32_32x32x16_bf16 v[64:79], v[154:157], v[114:117], v[64:79]
	ds_read_b64_tr_b16 v[150:151], v196 offset:32768
	ds_read_b64_tr_b16 v[152:153], v196 offset:34816
	ds_read_b64_tr_b16 v[154:155], v196 offset:36864
	ds_read_b64_tr_b16 v[156:157], v196 offset:38912
	s_waitcnt lgkmcnt(8)
	v_mfma_f32_32x32x16_bf16 v[80:95], v[158:161], v[110:113], v[80:95]
	v_mfma_f32_32x32x16_bf16 v[64:79], v[162:165], v[110:113], v[64:79]
	ds_read_b64_tr_b16 v[158:159], v196 offset:40960
	ds_read_b64_tr_b16 v[160:161], v196 offset:43008
	ds_read_b64_tr_b16 v[162:163], v196 offset:45056
	ds_read_b64_tr_b16 v[164:165], v196 offset:47104
	s_waitcnt lgkmcnt(10)
; #define SBAR() __builtin_amdgcn_sched_barrier(0)
; __device__ __forceinline__ void partialSM(f32x16& p0, f32x16& p1, float& m_reg, float& mn, float& alpha) {
;   constexpr float C = SCALE * 1.4426950408889634f;
;   float pmax = p0[0];
; #pragma unroll
;   for (int r = 1; r < 16; ++r) pmax = fmaxf(pmax, p0[r]);
; #pragma unroll
;   for (int r = 0; r < 16; ++r) pmax = fmaxf(pmax, p1[r]);
;   { auto rr = __builtin_amdgcn_permlane32_swap(__float_as_uint(pmax), __float_as_uint(pmax), false, false);
;     pmax = fmaxf(__uint_as_float(rr[0]), __uint_as_float(rr[1])); }
;   if (__builtin_expect(__all(pmax - m_reg <= THR / SCALE), 1)) { mn = m_reg; alpha = 1.f; }
;   else { mn = fmaxf(m_reg, pmax); alpha = __builtin_amdgcn_exp2f((m_reg - mn) * C); m_reg = mn; }
; template <int D0> __device__ __forceinline__ void pv_one(f32x16& od, int vb, bf16x8 pa0, bf16x8 pa1, bf16x8 pa2, bf16x8 pa3) {
;   const s16x4 l0 = tr_read<v_rd_off(D0, 0, 0)>(vb), h0 = tr_read<v_rd_off(D0, 0, 1)>(vb), l1 = tr_read<v_rd_off(D0, 1, 0)>(vb), h1 = tr_read<v_rd_off(D0, 1, 1)>(vb);
;   const s16x4 l2 = tr_read<v_rd_off(D0, 2, 0)>(vb), h2 = tr_read<v_rd_off(D0, 2, 1)>(vb), l3 = tr_read<v_rd_off(D0, 3, 0)>(vb), h3 = tr_read<v_rd_off(D0, 3, 1)>(vb);
;   asm volatile("s_waitcnt lgkmcnt(0)" ::: "memory"); SBAR();
;     ...
;   od = __builtin_amdgcn_mfma_f32_32x32x16_bf16(pa0, PK(l0, h0), od, 0, 0, 0);
;   od = __builtin_amdgcn_mfma_f32_32x32x16_bf16(pa1, PK(l1, h1), od, 0, 0, 0);
;   od = __builtin_amdgcn_mfma_f32_32x32x16_bf16(pa2, PK(l2, h2), od, 0, 0, 0);
;   od = __builtin_amdgcn_mfma_f32_32x32x16_bf16(pa3, PK(l3, h3), od, 0, 0, 0);
;     ...
; }
	v_mfma_f32_32x32x16_bf16 v[80:95], v[228:231], v[106:109], v[80:95]
	v_mfma_f32_32x32x16_bf16 v[64:79], v[232:235], v[106:109], v[64:79]
	ds_read_b64_tr_b16 v[228:229], v196 offset:33280
	ds_read_b64_tr_b16 v[230:231], v196 offset:35328
	ds_read_b64_tr_b16 v[232:233], v196 offset:37376
	ds_read_b64_tr_b16 v[234:235], v196 offset:39424
	s_waitcnt lgkmcnt(12)
	v_mfma_f32_32x32x16_bf16 v[80:95], v[236:239], v[102:105], v[80:95]
	v_mfma_f32_32x32x16_bf16 v[64:79], v[240:243], v[102:105], v[64:79]
	ds_read_b64_tr_b16 v[236:237], v196 offset:41472
	ds_read_b64_tr_b16 v[238:239], v196 offset:43520
	s_waitcnt lgkmcnt(12)
	v_mfma_f32_32x32x16_bf16 v[0:15], v[166:169], v[150:153], v[0:15]
	ds_read_b64_tr_b16 v[240:241], v196 offset:45568
	ds_read_b64_tr_b16 v[242:243], v196 offset:47616
	s_waitcnt lgkmcnt(12)
	v_mfma_f32_32x32x16_bf16 v[0:15], v[170:173], v[154:157], v[0:15]
	ds_read_b64_tr_b16 v[150:151], v196 offset:33792
	ds_read_b64_tr_b16 v[152:153], v196 offset:35840
	s_waitcnt lgkmcnt(12)
	v_mfma_f32_32x32x16_bf16 v[0:15], v[176:179], v[158:161], v[0:15]
	ds_read_b64_tr_b16 v[154:155], v196 offset:37888
	ds_read_b64_tr_b16 v[156:157], v196 offset:39936
	s_waitcnt lgkmcnt(12)
	v_mfma_f32_32x32x16_bf16 v[0:15], v[180:183], v[162:165], v[0:15]
	ds_read_b64_tr_b16 v[158:159], v196 offset:41984
	ds_read_b64_tr_b16 v[160:161], v196 offset:44032
	s_waitcnt lgkmcnt(12)
	v_mfma_f32_32x32x16_bf16 v[48:63], v[166:169], v[228:231], v[48:63]
	ds_read_b64_tr_b16 v[162:163], v196 offset:46080
	ds_read_b64_tr_b16 v[164:165], v196 offset:48128
	s_waitcnt lgkmcnt(12)
	v_mfma_f32_32x32x16_bf16 v[48:63], v[170:173], v[232:235], v[48:63]
	ds_read_b64_tr_b16 v[228:229], v196 offset:34304
	ds_read_b64_tr_b16 v[230:231], v196 offset:36352
	s_waitcnt lgkmcnt(12)
	v_mfma_f32_32x32x16_bf16 v[48:63], v[176:179], v[236:239], v[48:63]
	ds_read_b64_tr_b16 v[232:233], v196 offset:38400
	ds_read_b64_tr_b16 v[234:235], v196 offset:40448
	s_waitcnt lgkmcnt(12)
	v_mfma_f32_32x32x16_bf16 v[48:63], v[180:183], v[240:243], v[48:63]
	ds_read_b64_tr_b16 v[236:237], v196 offset:42496
	ds_read_b64_tr_b16 v[238:239], v196 offset:44544
	s_waitcnt lgkmcnt(12)
	v_mfma_f32_32x32x16_bf16 v[32:47], v[166:169], v[150:153], v[32:47]
	ds_read_b64_tr_b16 v[240:241], v196 offset:46592
	ds_read_b64_tr_b16 v[242:243], v196 offset:48640
	s_waitcnt lgkmcnt(12)
	v_mfma_f32_32x32x16_bf16 v[32:47], v[170:173], v[154:157], v[32:47]
	s_waitcnt lgkmcnt(10)
	v_mfma_f32_32x32x16_bf16 v[32:47], v[176:179], v[158:161], v[32:47]
	s_waitcnt lgkmcnt(8)
	v_mfma_f32_32x32x16_bf16 v[32:47], v[180:183], v[162:165], v[32:47]
	s_waitcnt lgkmcnt(6)
	v_mfma_f32_32x32x16_bf16 v[16:31], v[166:169], v[228:231], v[16:31]
	s_waitcnt lgkmcnt(4)
	v_mfma_f32_32x32x16_bf16 v[16:31], v[170:173], v[232:235], v[16:31]
	s_waitcnt lgkmcnt(2)
	v_mfma_f32_32x32x16_bf16 v[16:31], v[176:179], v[236:239], v[16:31]
	s_waitcnt lgkmcnt(0)
	v_mfma_f32_32x32x16_bf16 v[16:31], v[180:183], v[240:243], v[16:31]
	s_setprio 0
	s_barrier
	v_max3_f32 v190, v80, v81, v82
	v_max3_f32 v191, v64, v65, v66
	v_max3_f32 v190, v190, v83, v84
	v_max3_f32 v191, v191, v67, v68
	v_max3_f32 v190, v190, v85, v86
	v_max3_f32 v191, v191, v69, v70
	v_max3_f32 v190, v190, v87, v88
	v_max3_f32 v191, v191, v71, v72
	v_max3_f32 v190, v190, v89, v90
	v_max3_f32 v191, v191, v73, v74
	v_max3_f32 v190, v190, v91, v92
	v_max3_f32 v191, v191, v75, v76
	v_max3_f32 v190, v190, v93, v94
	v_max3_f32 v191, v191, v77, v78
	v_max3_f32 v190, v190, v95, v79
	v_max_f32_e32 v190, v190, v191
	v_sub_f32_e32 v215, v190, v174
	v_cmp_ge_f32_e32 vcc, s86, v215
	s_nop 3
	s_cmp_eq_u64 vcc, exec
	s_cbranch_scc1 .Lda_common_3
	v_mov_b32_e32 v191, v190
	s_nop 1
	v_permlane32_swap_b32_e32 v190, v191
	s_nop 0
	v_max_f32_e32 v212, v190, v191
	v_max_f32_e32 v191, v174, v212
	v_sub_f32_e32 v215, v174, v191
	v_mul_f32_e32 v215, s92, v215
	v_exp_f32_e32 v213, v215
	v_mov_b32_e32 v174, v191
	v_mul_f32_e32 v214, 0xbe0293ee, v174
	v_mul_f32_e32 v175, v175, v213
	s_and_saveexec_b64 s[12:13], s[40:41]
	ds_write_b32 v199, v213 offset:128
	s_or_b64 exec, exec, s[12:13]
	s_waitcnt lgkmcnt(0)
	v_add_u32_e32 v215, v99, v96
	ds_read_b128 v[228:231], v215 offset:128
	ds_read_b128 v[232:235], v215 offset:160
	ds_read_b128 v[236:239], v215 offset:192
	ds_read_b128 v[240:243], v215 offset:224
	s_waitcnt lgkmcnt(0)
	v_pk_mul_f32 v[0:1], v[0:1], v[228:229]
	v_pk_mul_f32 v[2:3], v[2:3], v[230:231]
	v_pk_mul_f32 v[4:5], v[4:5], v[232:233]
	v_pk_mul_f32 v[6:7], v[6:7], v[234:235]
	v_pk_mul_f32 v[8:9], v[8:9], v[236:237]
	v_pk_mul_f32 v[10:11], v[10:11], v[238:239]
	v_pk_mul_f32 v[12:13], v[12:13], v[240:241]
	v_pk_mul_f32 v[14:15], v[14:15], v[242:243]
	v_pk_mul_f32 v[48:49], v[48:49], v[228:229]
	v_pk_mul_f32 v[50:51], v[50:51], v[230:231]
	v_pk_mul_f32 v[52:53], v[52:53], v[232:233]
	v_pk_mul_f32 v[54:55], v[54:55], v[234:235]
	v_pk_mul_f32 v[56:57], v[56:57], v[236:237]
	v_pk_mul_f32 v[58:59], v[58:59], v[238:239]
	v_pk_mul_f32 v[60:61], v[60:61], v[240:241]
	v_pk_mul_f32 v[62:63], v[62:63], v[242:243]
	v_pk_mul_f32 v[32:33], v[32:33], v[228:229]
	v_pk_mul_f32 v[34:35], v[34:35], v[230:231]
	v_pk_mul_f32 v[36:37], v[36:37], v[232:233]
	v_pk_mul_f32 v[38:39], v[38:39], v[234:235]
	v_pk_mul_f32 v[40:41], v[40:41], v[236:237]
	v_pk_mul_f32 v[42:43], v[42:43], v[238:239]
	v_pk_mul_f32 v[44:45], v[44:45], v[240:241]
	v_pk_mul_f32 v[46:47], v[46:47], v[242:243]
	v_pk_mul_f32 v[16:17], v[16:17], v[228:229]
	v_pk_mul_f32 v[18:19], v[18:19], v[230:231]
	v_pk_mul_f32 v[20:21], v[20:21], v[232:233]
	v_pk_mul_f32 v[22:23], v[22:23], v[234:235]
	v_pk_mul_f32 v[24:25], v[24:25], v[236:237]
	v_pk_mul_f32 v[26:27], v[26:27], v[238:239]
	v_pk_mul_f32 v[28:29], v[28:29], v[240:241]
	v_pk_mul_f32 v[30:31], v[30:31], v[242:243]

; __device__ __forceinline__ void partialSM(f32x16& p0, f32x16& p1, float& m_reg, float& mn, float& alpha) {
;     ...
;   for (int r = 0; r < 16; ++r) p0[r] = __builtin_amdgcn_exp2f(p0[r]);
; }
; __device__ __forceinline__ void finishSM(f32x16& p0, f32x16& p1, float alpha, float& l_reg, bf16x8& pa0, bf16x8& pa1, bf16x8& pa2, bf16x8& pa3) {
; #pragma unroll
;   for (int r = 0; r < 16; ++r) p1[r] = __builtin_amdgcn_exp2f(p1[r]);
;   float ps = 0;
; #pragma unroll
;   for (int r = 0; r < 16; ++r) ps += p0[r];
; #pragma unroll
;   for (int r = 0; r < 16; ++r) ps += p1[r];
;   { auto rr = __builtin_amdgcn_permlane32_swap(__float_as_uint(ps), __float_as_uint(ps), false, false);
;     ps = __uint_as_float(rr[0]) + __uint_as_float(rr[1]); }
;   l_reg = l_reg * alpha + ps;
;     ...
;   PK4(p0, 0, pa0); PK4(p0, 8, pa1); PK4(p1, 0, pa2); PK4(p1, 8, pa3);
;     ...
; }
.Lda_noresc_3:
	v_exp_f32_e32 v80, v80
	v_exp_f32_e32 v81, v81
	v_exp_f32_e32 v82, v82
	v_exp_f32_e32 v83, v83
	v_exp_f32_e32 v84, v84
	v_exp_f32_e32 v85, v85
	v_exp_f32_e32 v86, v86
	v_exp_f32_e32 v87, v87
	v_exp_f32_e32 v88, v88
	v_exp_f32_e32 v89, v89
	v_exp_f32_e32 v90, v90
	v_exp_f32_e32 v91, v91
	v_exp_f32_e32 v92, v92
	v_exp_f32_e32 v93, v93
	v_exp_f32_e32 v94, v94
	v_exp_f32_e32 v95, v95
	v_exp_f32_e32 v64, v64
	v_exp_f32_e32 v65, v65
	v_exp_f32_e32 v66, v66
	v_exp_f32_e32 v67, v67
	v_exp_f32_e32 v68, v68
	v_exp_f32_e32 v69, v69
	v_exp_f32_e32 v70, v70
	v_exp_f32_e32 v71, v71
	v_exp_f32_e32 v72, v72
	v_exp_f32_e32 v73, v73
	v_exp_f32_e32 v74, v74
	v_exp_f32_e32 v75, v75
	v_exp_f32_e32 v76, v76
	v_exp_f32_e32 v77, v77
	v_exp_f32_e32 v78, v78
	v_exp_f32_e32 v79, v79
	v_add_f32_e32 v190, v80, v81
	v_add_f32_e32 v191, v82, v83
	v_add_f32_e32 v190, v190, v84
	v_add_f32_e32 v191, v191, v85
	v_add_f32_e32 v190, v190, v86
	v_add_f32_e32 v191, v191, v87
	v_add_f32_e32 v190, v190, v88
	v_add_f32_e32 v191, v191, v89
	v_add_f32_e32 v190, v190, v90
	v_add_f32_e32 v191, v191, v91
	v_add_f32_e32 v190, v190, v92
	v_add_f32_e32 v191, v191, v93
	v_add_f32_e32 v190, v190, v94
	v_add_f32_e32 v191, v191, v95
	v_add_f32_e32 v190, v190, v64
	v_add_f32_e32 v191, v191, v65
	v_add_f32_e32 v190, v190, v66
	v_add_f32_e32 v191, v191, v67
	v_add_f32_e32 v190, v190, v68
	v_add_f32_e32 v191, v191, v69
	v_add_f32_e32 v190, v190, v70
	v_add_f32_e32 v191, v191, v71
	v_add_f32_e32 v190, v190, v72
	v_add_f32_e32 v191, v191, v73
	v_add_f32_e32 v190, v190, v74
	v_add_f32_e32 v191, v191, v75
	v_add_f32_e32 v190, v190, v76
	v_add_f32_e32 v191, v191, v77
	v_add_f32_e32 v190, v190, v78
	v_add_f32_e32 v191, v191, v79
	v_add_f32_e32 v190, v190, v191
	v_cvt_pk_bf16_f32 v166, v80, v81
	v_cvt_pk_bf16_f32 v167, v82, v83
	v_cvt_pk_bf16_f32 v168, v84, v85
	v_cvt_pk_bf16_f32 v169, v86, v87
	v_cvt_pk_bf16_f32 v170, v88, v89
	v_cvt_pk_bf16_f32 v171, v90, v91
	v_cvt_pk_bf16_f32 v172, v92, v93
	v_cvt_pk_bf16_f32 v173, v94, v95
	v_cvt_pk_bf16_f32 v176, v64, v65
	v_cvt_pk_bf16_f32 v177, v66, v67
	v_cvt_pk_bf16_f32 v178, v68, v69
	v_cvt_pk_bf16_f32 v179, v70, v71
	v_cvt_pk_bf16_f32 v180, v72, v73
	v_cvt_pk_bf16_f32 v181, v74, v75
	v_cvt_pk_bf16_f32 v182, v76, v77
	v_cvt_pk_bf16_f32 v183, v78, v79
	s_nop 1
	v_permlane32_swap_b32_e32 v166, v168
	v_permlane32_swap_b32_e32 v167, v169
	v_permlane32_swap_b32_e32 v170, v172
	v_permlane32_swap_b32_e32 v171, v173
	v_permlane32_swap_b32_e32 v176, v178
	v_permlane32_swap_b32_e32 v177, v179
	v_permlane32_swap_b32_e32 v180, v182
	v_permlane32_swap_b32_e32 v181, v183
	v_add_f32_e32 v175, v175, v190
	s_add_u32 s31, s31, 1
	s_cmp_lt_u32 s31, 132
	s_cbranch_scc0 .Lda_skipk_3
	ds_read_b128 v[150:153], v204 offset:0
	ds_read_b128 v[154:157], v204 offset:8192
	ds_read_b128 v[158:161], v205 offset:0
	ds_read_b128 v[162:165], v205 offset:8192
	ds_read_b128 v[228:231], v206 offset:0
	ds_read_b128 v[232:235], v206 offset:8192
	ds_read_b128 v[236:239], v207 offset:0
	ds_read_b128 v[240:243], v207 offset:8192

; #define SBAR() __builtin_amdgcn_sched_barrier(0)
; #define RESC(a) do { if (__any((a) < 1.f)) { if (hi == 0) al_l[r32] = (a); asm volatile("s_waitcnt lgkmcnt(0)" ::: "memory"); \
;     _Pragma("unroll") for (int d = 0; d < 4; ++d) _Pragma("unroll") for (int r = 0; r < 16; ++r) o[d][r] *= al_l[crow(r, hi)]; } } while (0)
; template <int MODE, int SDEPTH>
; __device__ __forceinline__ void attn_unit(const UnitP& u, char* lds) {
;     ...
;   __syncthreads(); RESC(alB);
;   finishSM(pB0, pB1, alB, l_reg, pa0, pa1, pa2, pa3); SBAR();
;   pv_d0(o, vb0 + (int)SHM_V, pa0, pa1, pa2, pa3);
;   l_reg += __builtin_amdgcn_exp2f(u.sink_l2e - m_reg * (SCALE * 1.4426950408889634f));
;   if (hi == 0) li_l[r32] = l_reg; asm volatile("s_waitcnt lgkmcnt(0)" ::: "memory");
.Lda_trail:
	s_mov_b64 s[34:35], s[84:85]
	v_readlane_b32 s36, v254, 60
	v_mov_b32_e32 v191, v175
	s_nop 1
	v_permlane32_swap_b32_e32 v175, v191
	s_nop 0
	v_add_f32_e32 v175, v175, v191
	s_and_saveexec_b64 s[10:11], s[40:41]
	ds_write_b32 v199, v175
	s_branch .LBB0_523
